# scan y partial sums reduced by the helper waves; MLA V fragments prefetched ahead of the softmax
# speedup vs baseline: 1.0022x; 1.0022x over previous
; #define otid() otid_(wid_k)
; DI void scan_block(float* ldsf, const u16* __restrict__ R, const u16* __restrict__ KP, const u16* __restrict__ KK, const u16* __restrict__ KKA,
;                    const u16* __restrict__ V, const float* __restrict__ Wd, float* __restrict__ Y, int blk, int wid_k) {
;   const int tid = otid(), lane = tid & 63, w = tid >> 6;
;   const int bh = blk >> 2, rq = blk & 3, b = bh >> 2, h = bh & 3;
;   const int ks = lane & 15, rowl = (w & 3) * 4 + (lane >> 4);
;   const bool worker = (w < 4);
;   float* ybuf = ldsf + 2 * 16 * 336;
;   float S0 = 0.f, S1 = 0.f, S2 = 0.f, S3 = 0.f, yreg = 0.f;
;   const size_t tb = (size_t)b * SEQ;
;   const int hc = h * 64;
;   const int a0i = tid >> 7, a0step = (tid & 127) >> 3, a0c = (tid & 7) * 8;
;   const int wstep = (tid & 255) >> 4, wc = (tid & 15) * 4;
;   const int vstep = (tid & 31) >> 1, vhalf = tid & 1;
;     ...
;     if (tid < 256) {
;       const int step = tid >> 4, row = tid & 15;
;       Y[(tb + (size_t)c * 16 + step) * 256 + hc + rq * 16 + row] = yb[tid];
;     }
.LBB0_1280:
	s_or_b64 exec, exec, s[6:7]
	v_lshrrev_b32_e32 v15, 4, v69
	v_ashrrev_i32_e32 v22, 6, v69
	v_lshlrev_b32_e32 v23, 2, v22
	v_and_b32_e32 v15, 3, v15
	v_cmp_gt_i32_e64 s[6:7], 4, v22
	v_ashrrev_i32_e32 v22, 4, v69
	s_lshl_b64 s[64:65], s[60:61], 22
	v_and_or_b32 v24, v23, 12, v15
	v_ashrrev_i32_e32 v23, 31, v22
	s_add_u32 s66, s64, 0x88a0000
	s_addc_u32 s67, s65, 0
	v_lshlrev_b64 v[22:23], 10, v[22:23]
	v_lshl_add_u64 v[56:57], s[66:67], 0, v[22:23]
	s_lshl_b32 s66, s63, 6
	s_and_b32 s66, s66, 0x300
	s_and_b32 s67, s63, 3
	v_or_b32_e32 v15, s66, v56
	s_lshl_b32 s68, s67, 6
	s_lshl_b64 s[60:61], s[60:61], 21
	s_lshl_b32 s63, s63, 5
	v_or3_b32 v56, v15, s68, v70
	v_and_b32_e32 v98, 15, v69
	v_bfe_u32 v116, v69, 4, 4
	v_lshlrev_b32_e32 v117, 10, v98
	v_lshl_or_b32 v117, v116, 2, v117
	v_lshrrev_b32_e32 v116, 4, v69
	v_lshlrev_b32_e32 v116, 10, v116
	v_lshl_or_b32 v116, v98, 2, v116
	v_sub_u32_e32 v117, v117, v116
	v_cmp_lt_u32_e32 vcc, 0xff, v69
	s_nop 1
	v_cndmask_b32_e32 v117, 0, v117, vcc
	v_ashrrev_i32_e32 v116, 31, v117
	v_add_co_u32_e32 v56, vcc, v56, v117
	s_nop 1
	v_addc_co_u32_e32 v57, vcc, v57, v116, vcc
	v_lshl_or_b32 v15, v21, 9, s60
	s_and_b32 s72, s63, 0x180
	v_or_b32_e32 v15, s72, v15
	s_lshl_b32 s63, s67, 5
	v_or3_b32 v58, v15, s63, v14
	v_lshl_or_b32 v14, v19, 10, s64
	v_lshlrev_b32_e32 v15, 4, v18
	v_or3_b32 v60, v14, s66, v15
	v_lshl_add_u64 v[14:15], v[0:1], 0, s[60:61]
	v_lshlrev_b32_e32 v0, 9, v17
	v_lshl_add_u64 v[14:15], v[14:15], 0, v[0:1]
	v_and_b32_e32 v0, 7, v16
	v_lshl_add_u64 v[14:15], v[14:15], 0, s[72:73]
	v_lshlrev_b32_e32 v0, 4, v0
	v_lshlrev_b32_e32 v20, 6, v20
	v_lshl_add_u64 v[62:63], v[14:15], 0, v[0:1]
	v_mov_b32_e32 v14, 0
	v_cmp_eq_u32_e64 s[8:9], 15, v18
	v_lshlrev_b32_e32 v75, 6, v18
	s_mov_b32 s62, 0
	v_cmp_eq_u32_e64 s[10:11], 0, v18
	v_cmp_eq_u32_e64 s[12:13], 1, v18
	v_cmp_eq_u32_e64 s[14:15], 2, v18
	v_cmp_eq_u32_e64 s[16:17], 3, v18
	v_cmp_eq_u32_e64 s[18:19], 4, v18
	v_cmp_eq_u32_e64 s[20:21], 5, v18
	v_cmp_eq_u32_e64 s[22:23], 6, v18
	v_cmp_eq_u32_e64 s[24:25], 7, v18
	v_cmp_eq_u32_e64 s[26:27], 8, v18
	v_cmp_eq_u32_e64 s[28:29], 9, v18
	v_cmp_eq_u32_e64 s[30:31], 10, v18
	v_cmp_eq_u32_e64 s[34:35], 11, v18
	v_cmp_eq_u32_e64 s[36:37], 12, v18
	v_cmp_eq_u32_e64 s[38:39], 13, v18
	v_cmp_eq_u32_e64 s[40:41], 14, v18
	v_mov_b32_e32 v59, s61
	v_mov_b32_e32 v61, s65
	v_lshlrev_b32_e32 v76, 2, v24
	v_lshlrev_b32_e32 v77, 2, v20
	v_mov_b32_e32 v15, v14
	v_mov_b32_e32 v16, v14
	v_mov_b32_e32 v17, v14
	v_mov_b32_e32 v0, v14
	s_waitcnt lgkmcnt(0)
	s_barrier
	s_branch .LBB0_1282

; DI void scan_block(float* ldsf, const u16* __restrict__ R, const u16* __restrict__ KP, const u16* __restrict__ KK, const u16* __restrict__ KKA,
;                    const u16* __restrict__ V, const float* __restrict__ Wd, float* __restrict__ Y, int blk, int wid_k) {
;     ...
;     if (worker) {
;       typedef float f2 __attribute__((ext_vector_type(2)));
;       f2 Sa = {S0, S1}, Sb = {S2, S3};
;       float4 w4 = *(const float4*)(bp + ks * 4);
;       float4 kk4 = *(const float4*)(bp + 64 + ks * 4);
;       float4 ka4 = *(const float4*)(bp + 128 + ks * 4);
;       float4 kp4 = *(const float4*)(bp + 192 + ks * 4);
;       float4 r4 = *(const float4*)(bp + 256 + ks * 4);
;       float vv = bp[320 + rowl];
;       float yp = 0.f;
; #pragma unroll
;       for (int step = 0; step < 16; ++step) {
;         float4 w4n = w4, kk4n = kk4, ka4n = ka4, kp4n = kp4, r4n = r4; float vvn = vv;
;         if (step + 1 < 16) {
;           const float* sp = bp + (step + 1) * 336;
;           w4n = *(const float4*)(sp + ks * 4);
;           kk4n = *(const float4*)(sp + 64 + ks * 4);
;           ka4n = *(const float4*)(sp + 128 + ks * 4);
;           kp4n = *(const float4*)(sp + 192 + ks * 4);
;           r4n = *(const float4*)(sp + 256 + ks * 4);
;           vvn = sp[320 + rowl];
;         }
;         const f2 kka = {kk4.x, kk4.y}, kkb = {kk4.z, kk4.w}, wa = {w4.x, w4.y}, wb = {w4.z, w4.w};
;         const f2 kaa = {ka4.x, ka4.y}, kab = {ka4.z, ka4.w}, kpa = {kp4.x, kp4.y}, kpb = {kp4.z, kp4.w};
;         const f2 ra = {r4.x, r4.y}, rb = {r4.z, r4.w};
;         const f2 d2 = Sa * kka + Sb * kkb;
;         float d = d2.x + d2.y;
;         const f2 ta = Sa * wa + kpa * vv, tb = Sb * wb + kpb * vv;
;         d = dpp_add<0xB1>(d); yp = dpp_add<0xB1>(yp);
;         d = dpp_add<0x4E>(d); yp = dpp_add<0x4E>(yp);
;         d = dpp_add<0x141>(d); yp = dpp_add<0x141>(yp);
;         d = dpp_add<0x140>(d); yp = dpp_add<0x140>(yp);
.LBB0_1288:
	s_and_b32 s66, s62, 1
	s_mul_i32 s63, s66, 0x5400
	s_add_i32 s67, s63, 0
	s_mul_i32 s63, s66, 0xffffb000
	s_add_i32 s63, s67, s63
	s_and_saveexec_b64 s[64:65], s[6:7]
	s_cbranch_execz .LBB0_1290
	s_lshl_b32 s63, s66, 14
	s_add_i32 s63, s63, 0x10000
	v_lshl_add_u32 v99, v69, 2, s63
	v_lshl_add_u32 v79, v70, 2, s67
	ds_read_b128 v[18:21], v79
	ds_read_b128 v[22:25], v79 offset:256
	ds_read_b128 v[26:29], v79 offset:512
	ds_read_b128 v[30:33], v79 offset:768
	ds_read_b128 v[34:37], v79 offset:1024
	v_add_u32_e32 v78, s67, v76
	s_waitcnt lgkmcnt(3)
	v_pk_mul_f32 v[22:23], v[14:15], v[22:23]
	ds_read_b32 v68, v78 offset:1280
	ds_read_b128 v[38:41], v79 offset:1344
	ds_read_b128 v[42:45], v79 offset:1600
	ds_read_b128 v[46:49], v79 offset:1856
	ds_read_b128 v[50:53], v79 offset:2112
	ds_read_b128 v[64:67], v79 offset:2368
	ds_read_b32 v80, v78 offset:2624
	v_pk_fma_f32 v[22:23], v[16:17], v[24:25], v[22:23]
	s_nop 0
	v_add_f32_e32 v24, v22, v23
	s_waitcnt lgkmcnt(6)
	v_pk_mul_f32 v[22:23], v[30:31], v[68:69] op_sel_hi:[1,0]
	s_nop 0
	v_pk_fma_f32 v[14:15], v[14:15], v[18:19], v[22:23]
	v_pk_mul_f32 v[18:19], v[32:33], v[68:69] op_sel_hi:[1,0]
	s_nop 0
	v_pk_fma_f32 v[16:17], v[16:17], v[20:21], v[18:19]
	v_add_f32_dpp v18, v24, v24 quad_perm:[1,0,3,2] row_mask:0xf bank_mask:0xf bound_ctrl:1
	s_nop 1
	v_add_f32_dpp v18, v18, v18 quad_perm:[2,3,0,1] row_mask:0xf bank_mask:0xf bound_ctrl:1
	s_nop 1
	v_add_f32_dpp v18, v18, v18 row_half_mirror row_mask:0xf bank_mask:0xf bound_ctrl:1
	s_nop 1
	v_add_f32_dpp v18, v18, v18 row_mirror row_mask:0xf bank_mask:0xf bound_ctrl:1
	v_pk_fma_f32 v[84:85], v[28:29], v[18:19], v[16:17] op_sel_hi:[1,0,1] neg_lo:[1,0,0] neg_hi:[1,0,0]
	v_pk_fma_f32 v[82:83], v[26:27], v[18:19], v[14:15] op_sel_hi:[1,0,1] neg_lo:[1,0,0] neg_hi:[1,0,0]
	v_pk_mul_f32 v[14:15], v[36:37], v[84:85]
	s_waitcnt lgkmcnt(5)
	v_pk_mul_f32 v[36:37], v[40:41], v[84:85]
	v_pk_fma_f32 v[14:15], v[34:35], v[82:83], v[14:15]
	s_waitcnt lgkmcnt(4)
	v_pk_mul_f32 v[34:35], v[42:43], v[82:83]
	v_add_f32_e32 v81, v14, v15
	ds_write_b32 v99, v81
	v_pk_fma_f32 v[34:35], v[44:45], v[84:85], v[34:35]
	s_waitcnt lgkmcnt(0)
	v_pk_fma_f32 v[36:37], v[52:53], v[80:81], v[36:37] op_sel_hi:[1,0,1]
	v_add_f32_e32 v42, v34, v35
	v_pk_mul_f32 v[34:35], v[38:39], v[82:83]
	s_nop 0
	v_add_f32_dpp v38, v42, v42 quad_perm:[1,0,3,2] row_mask:0xf bank_mask:0xf bound_ctrl:1
	v_pk_fma_f32 v[34:35], v[50:51], v[80:81], v[34:35] op_sel_hi:[1,0,1]
	s_nop 0
	v_add_f32_dpp v38, v38, v38 quad_perm:[2,3,0,1] row_mask:0xf bank_mask:0xf bound_ctrl:1
	ds_read_b128 v[14:17], v79 offset:2688
	ds_read_b128 v[18:21], v79 offset:2944
	ds_read_b128 v[22:25], v79 offset:3200
	ds_read_b128 v[26:29], v79 offset:3456
	ds_read_b128 v[30:33], v79 offset:3712
	ds_read_b32 v68, v78 offset:3968
	v_add_f32_dpp v38, v38, v38 row_half_mirror row_mask:0xf bank_mask:0xf bound_ctrl:1
	s_nop 0
	s_nop 0
	v_add_f32_dpp v38, v38, v38 row_mirror row_mask:0xf bank_mask:0xf bound_ctrl:1
	v_pk_fma_f32 v[80:81], v[46:47], v[38:39], v[34:35] op_sel_hi:[1,0,1] neg_lo:[1,0,0] neg_hi:[1,0,0]
	v_pk_fma_f32 v[82:83], v[48:49], v[38:39], v[36:37] op_sel_hi:[1,0,1] neg_lo:[1,0,0] neg_hi:[1,0,0]
	s_waitcnt lgkmcnt(4)
	v_pk_mul_f32 v[18:19], v[18:19], v[80:81]
	v_pk_mul_f32 v[34:35], v[66:67], v[82:83]
	v_pk_fma_f32 v[18:19], v[20:21], v[82:83], v[18:19]
	v_pk_fma_f32 v[34:35], v[64:65], v[80:81], v[34:35]
	v_add_f32_e32 v18, v18, v19
	v_add_f32_e32 v64, v34, v35
	ds_write_b32 v99, v64 offset:1024
	v_pk_mul_f32 v[14:15], v[14:15], v[80:81]
	v_add_f32_dpp v18, v18, v18 quad_perm:[1,0,3,2] row_mask:0xf bank_mask:0xf bound_ctrl:1
	s_nop 1
	v_add_f32_dpp v18, v18, v18 quad_perm:[2,3,0,1] row_mask:0xf bank_mask:0xf bound_ctrl:1
	ds_read_b128 v[34:37], v79 offset:4032
	ds_read_b128 v[38:41], v79 offset:4288
	ds_read_b128 v[42:45], v79 offset:4544
	ds_read_b128 v[46:49], v79 offset:4800
	ds_read_b128 v[50:53], v79 offset:5056
	ds_read_b32 v0, v78 offset:5312
	v_add_f32_dpp v18, v18, v18 row_half_mirror row_mask:0xf bank_mask:0xf bound_ctrl:1
	s_waitcnt lgkmcnt(6)
	v_pk_fma_f32 v[14:15], v[26:27], v[68:69], v[14:15] op_sel_hi:[1,0,1]
	v_pk_mul_f32 v[16:17], v[16:17], v[82:83]
	v_add_f32_dpp v18, v18, v18 row_mirror row_mask:0xf bank_mask:0xf bound_ctrl:1
	v_pk_fma_f32 v[16:17], v[28:29], v[68:69], v[16:17] op_sel_hi:[1,0,1]
	v_pk_fma_f32 v[64:65], v[22:23], v[18:19], v[14:15] op_sel_hi:[1,0,1] neg_lo:[1,0,0] neg_hi:[1,0,0]
	v_pk_fma_f32 v[66:67], v[24:25], v[18:19], v[16:17] op_sel_hi:[1,0,1] neg_lo:[1,0,0] neg_hi:[1,0,0]
	s_waitcnt lgkmcnt(4)
	v_pk_mul_f32 v[38:39], v[38:39], v[64:65]
	v_pk_mul_f32 v[34:35], v[34:35], v[64:65]
	v_pk_fma_f32 v[38:39], v[40:41], v[66:67], v[38:39]
	v_pk_mul_f32 v[36:37], v[36:37], v[66:67]
	v_add_f32_e32 v38, v38, v39
	s_waitcnt lgkmcnt(0)
	v_pk_fma_f32 v[34:35], v[46:47], v[0:1], v[34:35] op_sel_hi:[1,0,1]
	v_pk_fma_f32 v[36:37], v[48:49], v[0:1], v[36:37] op_sel_hi:[1,0,1]
	v_add_f32_dpp v0, v38, v38 quad_perm:[1,0,3,2] row_mask:0xf bank_mask:0xf bound_ctrl:1
	v_pk_mul_f32 v[14:15], v[32:33], v[66:67]
	s_nop 0
	v_add_f32_dpp v0, v0, v0 quad_perm:[2,3,0,1] row_mask:0xf bank_mask:0xf bound_ctrl:1
	v_pk_fma_f32 v[14:15], v[30:31], v[64:65], v[14:15]
	s_nop 0
	v_add_f32_dpp v0, v0, v0 row_half_mirror row_mask:0xf bank_mask:0xf bound_ctrl:1
	v_add_f32_e32 v81, v14, v15
	ds_write_b32 v99, v81 offset:2048
	ds_read_b128 v[14:17], v79 offset:5376
	ds_read_b128 v[18:21], v79 offset:5632
	ds_read_b128 v[22:25], v79 offset:5888
	ds_read_b128 v[26:29], v79 offset:6144
	ds_read_b128 v[30:33], v79 offset:6400
	ds_read_b32 v68, v78 offset:6656
	v_add_f32_dpp v0, v0, v0 row_mirror row_mask:0xf bank_mask:0xf bound_ctrl:1
	v_pk_fma_f32 v[64:65], v[42:43], v[0:1], v[34:35] op_sel_hi:[1,0,1] neg_lo:[1,0,0] neg_hi:[1,0,0]
	v_pk_fma_f32 v[66:67], v[44:45], v[0:1], v[36:37] op_sel_hi:[1,0,1] neg_lo:[1,0,0] neg_hi:[1,0,0]
	s_waitcnt lgkmcnt(4)
; DI void scan_block(float* ldsf, const u16* __restrict__ R, const u16* __restrict__ KP, const u16* __restrict__ KK, const u16* __restrict__ KKA,
;                    const u16* __restrict__ V, const float* __restrict__ Wd, float* __restrict__ Y, int blk, int wid_k) {
;     ...
;       for (int step = 0; step < 16; ++step) {
;         float4 w4n = w4, kk4n = kk4, ka4n = ka4, kp4n = kp4, r4n = r4; float vvn = vv;
;         if (step + 1 < 16) {
;           const float* sp = bp + (step + 1) * 336;
;           w4n = *(const float4*)(sp + ks * 4);
;           kk4n = *(const float4*)(sp + 64 + ks * 4);
;           ka4n = *(const float4*)(sp + 128 + ks * 4);
;           kp4n = *(const float4*)(sp + 192 + ks * 4);
;           r4n = *(const float4*)(sp + 256 + ks * 4);
;           vvn = sp[320 + rowl];
;         }
;         const f2 kka = {kk4.x, kk4.y}, kkb = {kk4.z, kk4.w}, wa = {w4.x, w4.y}, wb = {w4.z, w4.w};
;         const f2 kaa = {ka4.x, ka4.y}, kab = {ka4.z, ka4.w}, kpa = {kp4.x, kp4.y}, kpb = {kp4.z, kp4.w};
;         const f2 ra = {r4.x, r4.y}, rb = {r4.z, r4.w};
;         const f2 d2 = Sa * kka + Sb * kkb;
;         float d = d2.x + d2.y;
;         const f2 ta = Sa * wa + kpa * vv, tb = Sb * wb + kpb * vv;
;         d = dpp_add<0xB1>(d); yp = dpp_add<0xB1>(yp);
;         d = dpp_add<0x4E>(d); yp = dpp_add<0x4E>(yp);
;         d = dpp_add<0x141>(d); yp = dpp_add<0x141>(yp);
;         d = dpp_add<0x140>(d); yp = dpp_add<0x140>(yp);
;         if (step > 0) yreg = (ks == step - 1) ? yp : yreg;
;         Sa = ta - kaa * d; Sb = tb - kab * d;
;         const f2 y2 = Sa * ra + Sb * rb;
;         yp = y2.x + y2.y;
	v_pk_mul_f32 v[18:19], v[18:19], v[64:65]
	v_pk_mul_f32 v[34:35], v[52:53], v[66:67]
	v_pk_fma_f32 v[18:19], v[20:21], v[66:67], v[18:19]
	v_pk_fma_f32 v[34:35], v[50:51], v[64:65], v[34:35]
	v_add_f32_e32 v18, v18, v19
	v_add_f32_e32 v0, v34, v35
	ds_write_b32 v99, v0 offset:3072
	v_add_f32_dpp v18, v18, v18 quad_perm:[1,0,3,2] row_mask:0xf bank_mask:0xf bound_ctrl:1
	s_nop 1
	v_add_f32_dpp v18, v18, v18 quad_perm:[2,3,0,1] row_mask:0xf bank_mask:0xf bound_ctrl:1
	v_pk_mul_f32 v[14:15], v[14:15], v[64:65]
	v_pk_mul_f32 v[16:17], v[16:17], v[66:67]
	v_add_f32_dpp v18, v18, v18 row_half_mirror row_mask:0xf bank_mask:0xf bound_ctrl:1
	s_waitcnt lgkmcnt(0)
	v_pk_fma_f32 v[14:15], v[26:27], v[68:69], v[14:15] op_sel_hi:[1,0,1]
	v_pk_fma_f32 v[16:17], v[28:29], v[68:69], v[16:17] op_sel_hi:[1,0,1]
	v_add_f32_dpp v0, v18, v18 row_mirror row_mask:0xf bank_mask:0xf bound_ctrl:1
	ds_read_b128 v[34:37], v79 offset:6720
	ds_read_b128 v[38:41], v79 offset:6976
	ds_read_b128 v[42:45], v79 offset:7232
	ds_read_b128 v[46:49], v79 offset:7488
	ds_read_b128 v[50:53], v79 offset:7744
	ds_read_b32 v80, v78 offset:8000
	v_pk_fma_f32 v[64:65], v[22:23], v[0:1], v[14:15] op_sel_hi:[1,0,1] neg_lo:[1,0,0] neg_hi:[1,0,0]
	v_pk_fma_f32 v[66:67], v[24:25], v[0:1], v[16:17] op_sel_hi:[1,0,1] neg_lo:[1,0,0] neg_hi:[1,0,0]
	s_waitcnt lgkmcnt(4)
	v_pk_mul_f32 v[38:39], v[38:39], v[64:65]
	v_pk_mul_f32 v[14:15], v[32:33], v[66:67]
	v_pk_fma_f32 v[14:15], v[30:31], v[64:65], v[14:15]
	v_pk_fma_f32 v[38:39], v[40:41], v[66:67], v[38:39]
	v_add_f32_e32 v81, v14, v15
	ds_write_b32 v99, v81 offset:4096
	v_add_f32_e32 v38, v38, v39
	v_pk_mul_f32 v[34:35], v[34:35], v[64:65]
	s_nop 0
	v_add_f32_dpp v38, v38, v38 quad_perm:[1,0,3,2] row_mask:0xf bank_mask:0xf bound_ctrl:1
	ds_read_b128 v[22:25], v79 offset:8064
	ds_read_b128 v[30:33], v79 offset:8320
	ds_read_b128 v[14:17], v79 offset:8576
	ds_read_b128 v[26:29], v79 offset:8832
	ds_read_b128 v[18:21], v79 offset:9088
	ds_read_b32 v0, v78 offset:9344
	v_add_f32_dpp v38, v38, v38 quad_perm:[2,3,0,1] row_mask:0xf bank_mask:0xf bound_ctrl:1
	s_waitcnt lgkmcnt(6)
	v_pk_fma_f32 v[34:35], v[46:47], v[80:81], v[34:35] op_sel_hi:[1,0,1]
	v_add_f32_dpp v38, v38, v38 row_half_mirror row_mask:0xf bank_mask:0xf bound_ctrl:1
	v_pk_mul_f32 v[36:37], v[36:37], v[66:67]
	s_nop 0
	v_add_f32_dpp v38, v38, v38 row_mirror row_mask:0xf bank_mask:0xf bound_ctrl:1
	v_pk_fma_f32 v[36:37], v[48:49], v[80:81], v[36:37] op_sel_hi:[1,0,1]
	v_pk_fma_f32 v[66:67], v[42:43], v[38:39], v[34:35] op_sel_hi:[1,0,1] neg_lo:[1,0,0] neg_hi:[1,0,0]
	v_pk_fma_f32 v[64:65], v[44:45], v[38:39], v[36:37] op_sel_hi:[1,0,1] neg_lo:[1,0,0] neg_hi:[1,0,0]
	s_waitcnt lgkmcnt(4)
	v_pk_mul_f32 v[30:31], v[30:31], v[66:67]
	v_pk_mul_f32 v[22:23], v[22:23], v[66:67]
	v_pk_fma_f32 v[30:31], v[32:33], v[64:65], v[30:31]
	v_pk_mul_f32 v[24:25], v[24:25], v[64:65]
	v_add_f32_e32 v30, v30, v31
	s_waitcnt lgkmcnt(0)
	v_pk_fma_f32 v[22:23], v[26:27], v[0:1], v[22:23] op_sel_hi:[1,0,1]
	v_pk_fma_f32 v[24:25], v[28:29], v[0:1], v[24:25] op_sel_hi:[1,0,1]
	v_add_f32_dpp v0, v30, v30 quad_perm:[1,0,3,2] row_mask:0xf bank_mask:0xf bound_ctrl:1
	v_pk_mul_f32 v[34:35], v[52:53], v[64:65]
	s_nop 0
	v_add_f32_dpp v0, v0, v0 quad_perm:[2,3,0,1] row_mask:0xf bank_mask:0xf bound_ctrl:1
	v_pk_fma_f32 v[34:35], v[50:51], v[66:67], v[34:35]
	s_nop 0
	v_add_f32_dpp v0, v0, v0 row_half_mirror row_mask:0xf bank_mask:0xf bound_ctrl:1
	v_add_f32_e32 v81, v34, v35
	ds_write_b32 v99, v81 offset:5120
	ds_read_b128 v[42:45], v79 offset:9408
	ds_read_b128 v[50:53], v79 offset:9664
	ds_read_b128 v[34:37], v79 offset:9920
	ds_read_b128 v[46:49], v79 offset:10176
	ds_read_b128 v[38:41], v79 offset:10432
	ds_read_b32 v68, v78 offset:10688
	v_add_f32_dpp v0, v0, v0 row_mirror row_mask:0xf bank_mask:0xf bound_ctrl:1
	v_pk_fma_f32 v[64:65], v[14:15], v[0:1], v[22:23] op_sel_hi:[1,0,1] neg_lo:[1,0,0] neg_hi:[1,0,0]
	v_pk_fma_f32 v[66:67], v[16:17], v[0:1], v[24:25] op_sel_hi:[1,0,1] neg_lo:[1,0,0] neg_hi:[1,0,0]
	s_waitcnt lgkmcnt(4)
	v_pk_mul_f32 v[50:51], v[50:51], v[64:65]
	v_pk_mul_f32 v[14:15], v[20:21], v[66:67]
	v_pk_fma_f32 v[50:51], v[52:53], v[66:67], v[50:51]
	v_pk_fma_f32 v[14:15], v[18:19], v[64:65], v[14:15]
	v_add_f32_e32 v81, v14, v15
	ds_write_b32 v99, v81 offset:6144
	v_add_f32_e32 v50, v50, v51
	v_pk_mul_f32 v[42:43], v[42:43], v[64:65]
	s_waitcnt lgkmcnt(0)
	v_pk_fma_f32 v[42:43], v[46:47], v[68:69], v[42:43] op_sel_hi:[1,0,1]
	v_add_f32_dpp v46, v50, v50 quad_perm:[1,0,3,2] row_mask:0xf bank_mask:0xf bound_ctrl:1
	s_nop 1
	v_add_f32_dpp v46, v46, v46 quad_perm:[2,3,0,1] row_mask:0xf bank_mask:0xf bound_ctrl:1
	s_nop 1
	v_add_f32_dpp v46, v46, v46 row_half_mirror row_mask:0xf bank_mask:0xf bound_ctrl:1
	ds_read_b128 v[14:17], v79 offset:10752
	ds_read_b128 v[18:21], v79 offset:11008
	ds_read_b128 v[22:25], v79 offset:11264
	ds_read_b128 v[26:29], v79 offset:11520
	ds_read_b128 v[30:33], v79 offset:11776
	ds_read_b32 v0, v78 offset:12032
	v_pk_mul_f32 v[44:45], v[44:45], v[66:67]
	v_add_f32_dpp v46, v46, v46 row_mirror row_mask:0xf bank_mask:0xf bound_ctrl:1
	v_pk_fma_f32 v[44:45], v[48:49], v[68:69], v[44:45] op_sel_hi:[1,0,1]
	v_pk_fma_f32 v[64:65], v[34:35], v[46:47], v[42:43] op_sel_hi:[1,0,1] neg_lo:[1,0,0] neg_hi:[1,0,0]
	v_pk_fma_f32 v[66:67], v[36:37], v[46:47], v[44:45] op_sel_hi:[1,0,1] neg_lo:[1,0,0] neg_hi:[1,0,0]
	s_waitcnt lgkmcnt(4)
	v_pk_mul_f32 v[18:19], v[18:19], v[64:65]
	v_pk_mul_f32 v[14:15], v[14:15], v[64:65]
	v_pk_fma_f32 v[18:19], v[20:21], v[66:67], v[18:19]
	v_pk_mul_f32 v[16:17], v[16:17], v[66:67]
	v_add_f32_e32 v18, v18, v19
	s_waitcnt lgkmcnt(0)
; DI void scan_block(float* ldsf, const u16* __restrict__ R, const u16* __restrict__ KP, const u16* __restrict__ KK, const u16* __restrict__ KKA,
;                    const u16* __restrict__ V, const float* __restrict__ Wd, float* __restrict__ Y, int blk, int wid_k) {
;     ...
;       for (int step = 0; step < 16; ++step) {
;         float4 w4n = w4, kk4n = kk4, ka4n = ka4, kp4n = kp4, r4n = r4; float vvn = vv;
;         if (step + 1 < 16) {
;           const float* sp = bp + (step + 1) * 336;
;           w4n = *(const float4*)(sp + ks * 4);
;           kk4n = *(const float4*)(sp + 64 + ks * 4);
;           ka4n = *(const float4*)(sp + 128 + ks * 4);
;           kp4n = *(const float4*)(sp + 192 + ks * 4);
;           r4n = *(const float4*)(sp + 256 + ks * 4);
;           vvn = sp[320 + rowl];
;         }
;         const f2 kka = {kk4.x, kk4.y}, kkb = {kk4.z, kk4.w}, wa = {w4.x, w4.y}, wb = {w4.z, w4.w};
;         const f2 kaa = {ka4.x, ka4.y}, kab = {ka4.z, ka4.w}, kpa = {kp4.x, kp4.y}, kpb = {kp4.z, kp4.w};
;         const f2 ra = {r4.x, r4.y}, rb = {r4.z, r4.w};
;         const f2 d2 = Sa * kka + Sb * kkb;
;         float d = d2.x + d2.y;
;         const f2 ta = Sa * wa + kpa * vv, tb = Sb * wb + kpb * vv;
;         d = dpp_add<0xB1>(d); yp = dpp_add<0xB1>(yp);
;         d = dpp_add<0x4E>(d); yp = dpp_add<0x4E>(yp);
;         d = dpp_add<0x141>(d); yp = dpp_add<0x141>(yp);
;         d = dpp_add<0x140>(d); yp = dpp_add<0x140>(yp);
;         if (step > 0) yreg = (ks == step - 1) ? yp : yreg;
;         Sa = ta - kaa * d; Sb = tb - kab * d;
;         const f2 y2 = Sa * ra + Sb * rb;
;         yp = y2.x + y2.y;
	v_pk_fma_f32 v[14:15], v[26:27], v[0:1], v[14:15] op_sel_hi:[1,0,1]
	v_pk_fma_f32 v[16:17], v[28:29], v[0:1], v[16:17] op_sel_hi:[1,0,1]
	v_add_f32_dpp v0, v18, v18 quad_perm:[1,0,3,2] row_mask:0xf bank_mask:0xf bound_ctrl:1
	v_pk_mul_f32 v[34:35], v[40:41], v[66:67]
	s_nop 0
	v_add_f32_dpp v0, v0, v0 quad_perm:[2,3,0,1] row_mask:0xf bank_mask:0xf bound_ctrl:1
	v_pk_fma_f32 v[34:35], v[38:39], v[64:65], v[34:35]
	s_nop 0
	v_add_f32_dpp v0, v0, v0 row_half_mirror row_mask:0xf bank_mask:0xf bound_ctrl:1
	v_add_f32_e32 v81, v34, v35
	ds_write_b32 v99, v81 offset:7168
	ds_read_b128 v[34:37], v79 offset:12096
	ds_read_b128 v[38:41], v79 offset:12352
	ds_read_b128 v[42:45], v79 offset:12608
	ds_read_b128 v[46:49], v79 offset:12864
	ds_read_b128 v[50:53], v79 offset:13120
	ds_read_b32 v68, v78 offset:13376
	v_add_f32_dpp v0, v0, v0 row_mirror row_mask:0xf bank_mask:0xf bound_ctrl:1
	v_pk_fma_f32 v[64:65], v[22:23], v[0:1], v[14:15] op_sel_hi:[1,0,1] neg_lo:[1,0,0] neg_hi:[1,0,0]
	v_pk_fma_f32 v[66:67], v[24:25], v[0:1], v[16:17] op_sel_hi:[1,0,1] neg_lo:[1,0,0] neg_hi:[1,0,0]
	s_waitcnt lgkmcnt(4)
	v_pk_mul_f32 v[38:39], v[38:39], v[64:65]
	v_pk_mul_f32 v[14:15], v[32:33], v[66:67]
	v_pk_fma_f32 v[38:39], v[40:41], v[66:67], v[38:39]
	v_pk_fma_f32 v[14:15], v[30:31], v[64:65], v[14:15]
	v_add_f32_e32 v81, v14, v15
	ds_write_b32 v99, v81 offset:8192
	v_add_f32_e32 v38, v38, v39
	s_nop 1
	v_add_f32_dpp v38, v38, v38 quad_perm:[1,0,3,2] row_mask:0xf bank_mask:0xf bound_ctrl:1
	s_nop 1
	v_add_f32_dpp v38, v38, v38 quad_perm:[2,3,0,1] row_mask:0xf bank_mask:0xf bound_ctrl:1
	v_pk_mul_f32 v[34:35], v[34:35], v[64:65]
	s_nop 0
	v_add_f32_dpp v38, v38, v38 row_half_mirror row_mask:0xf bank_mask:0xf bound_ctrl:1
	ds_read_b128 v[14:17], v79 offset:13440
	ds_read_b128 v[18:21], v79 offset:13696
	ds_read_b128 v[22:25], v79 offset:13952
	ds_read_b128 v[26:29], v79 offset:14208
	ds_read_b128 v[30:33], v79 offset:14464
	ds_read_b32 v0, v78 offset:14720
	s_waitcnt lgkmcnt(6)
	v_pk_fma_f32 v[34:35], v[46:47], v[68:69], v[34:35] op_sel_hi:[1,0,1]
	v_pk_mul_f32 v[36:37], v[36:37], v[66:67]
	v_add_f32_dpp v38, v38, v38 row_mirror row_mask:0xf bank_mask:0xf bound_ctrl:1
	v_pk_fma_f32 v[36:37], v[48:49], v[68:69], v[36:37] op_sel_hi:[1,0,1]
	v_pk_fma_f32 v[64:65], v[42:43], v[38:39], v[34:35] op_sel_hi:[1,0,1] neg_lo:[1,0,0] neg_hi:[1,0,0]
	v_pk_fma_f32 v[66:67], v[44:45], v[38:39], v[36:37] op_sel_hi:[1,0,1] neg_lo:[1,0,0] neg_hi:[1,0,0]
	s_waitcnt lgkmcnt(4)
	v_pk_mul_f32 v[18:19], v[18:19], v[64:65]
	v_pk_mul_f32 v[14:15], v[14:15], v[64:65]
	v_pk_fma_f32 v[18:19], v[20:21], v[66:67], v[18:19]
	v_pk_mul_f32 v[16:17], v[16:17], v[66:67]
	v_add_f32_e32 v18, v18, v19
	s_waitcnt lgkmcnt(0)
	v_pk_fma_f32 v[14:15], v[26:27], v[0:1], v[14:15] op_sel_hi:[1,0,1]
	v_pk_fma_f32 v[16:17], v[28:29], v[0:1], v[16:17] op_sel_hi:[1,0,1]
	v_add_f32_dpp v0, v18, v18 quad_perm:[1,0,3,2] row_mask:0xf bank_mask:0xf bound_ctrl:1
	v_pk_mul_f32 v[34:35], v[52:53], v[66:67]
	s_nop 0
	v_add_f32_dpp v0, v0, v0 quad_perm:[2,3,0,1] row_mask:0xf bank_mask:0xf bound_ctrl:1
	v_pk_fma_f32 v[34:35], v[50:51], v[64:65], v[34:35]
	s_nop 0
	v_add_f32_dpp v0, v0, v0 row_half_mirror row_mask:0xf bank_mask:0xf bound_ctrl:1
	v_add_f32_e32 v81, v34, v35
	ds_write_b32 v99, v81 offset:9216
	ds_read_b128 v[34:37], v79 offset:14784
	ds_read_b128 v[38:41], v79 offset:15040
	ds_read_b128 v[42:45], v79 offset:15296
	ds_read_b128 v[46:49], v79 offset:15552
	ds_read_b128 v[50:53], v79 offset:15808
	ds_read_b32 v68, v78 offset:16064
	v_add_f32_dpp v0, v0, v0 row_mirror row_mask:0xf bank_mask:0xf bound_ctrl:1
	v_pk_fma_f32 v[64:65], v[22:23], v[0:1], v[14:15] op_sel_hi:[1,0,1] neg_lo:[1,0,0] neg_hi:[1,0,0]
	v_pk_fma_f32 v[66:67], v[24:25], v[0:1], v[16:17] op_sel_hi:[1,0,1] neg_lo:[1,0,0] neg_hi:[1,0,0]
	s_waitcnt lgkmcnt(4)
	v_pk_mul_f32 v[38:39], v[38:39], v[64:65]
	v_pk_mul_f32 v[14:15], v[32:33], v[66:67]
	v_pk_fma_f32 v[38:39], v[40:41], v[66:67], v[38:39]
	v_pk_fma_f32 v[14:15], v[30:31], v[64:65], v[14:15]
	v_add_f32_e32 v81, v14, v15
	ds_write_b32 v99, v81 offset:10240
	v_add_f32_e32 v38, v38, v39
	s_nop 1
	v_add_f32_dpp v38, v38, v38 quad_perm:[1,0,3,2] row_mask:0xf bank_mask:0xf bound_ctrl:1
	s_nop 1
	v_add_f32_dpp v38, v38, v38 quad_perm:[2,3,0,1] row_mask:0xf bank_mask:0xf bound_ctrl:1
	v_pk_mul_f32 v[34:35], v[34:35], v[64:65]
	s_nop 0
	v_add_f32_dpp v38, v38, v38 row_half_mirror row_mask:0xf bank_mask:0xf bound_ctrl:1
	ds_read_b128 v[14:17], v79 offset:16128
	ds_read_b128 v[18:21], v79 offset:16384
	ds_read_b128 v[22:25], v79 offset:16640
	ds_read_b128 v[26:29], v79 offset:16896
	ds_read_b128 v[30:33], v79 offset:17152
	ds_read_b32 v0, v78 offset:17408
	s_waitcnt lgkmcnt(6)
	v_pk_fma_f32 v[34:35], v[46:47], v[68:69], v[34:35] op_sel_hi:[1,0,1]
	v_pk_mul_f32 v[36:37], v[36:37], v[66:67]
	v_add_f32_dpp v38, v38, v38 row_mirror row_mask:0xf bank_mask:0xf bound_ctrl:1
	v_pk_fma_f32 v[36:37], v[48:49], v[68:69], v[36:37] op_sel_hi:[1,0,1]
	v_pk_fma_f32 v[64:65], v[42:43], v[38:39], v[34:35] op_sel_hi:[1,0,1] neg_lo:[1,0,0] neg_hi:[1,0,0]
	v_pk_fma_f32 v[66:67], v[44:45], v[38:39], v[36:37] op_sel_hi:[1,0,1] neg_lo:[1,0,0] neg_hi:[1,0,0]
	s_waitcnt lgkmcnt(4)
	v_pk_mul_f32 v[18:19], v[18:19], v[64:65]
	v_pk_mul_f32 v[14:15], v[14:15], v[64:65]
	v_pk_fma_f32 v[18:19], v[20:21], v[66:67], v[18:19]
	v_pk_mul_f32 v[16:17], v[16:17], v[66:67]
	v_add_f32_e32 v18, v18, v19
	s_waitcnt lgkmcnt(0)
; DI void scan_block(float* ldsf, const u16* __restrict__ R, const u16* __restrict__ KP, const u16* __restrict__ KK, const u16* __restrict__ KKA,
;                    const u16* __restrict__ V, const float* __restrict__ Wd, float* __restrict__ Y, int blk, int wid_k) {
;     ...
;       for (int step = 0; step < 16; ++step) {
;         float4 w4n = w4, kk4n = kk4, ka4n = ka4, kp4n = kp4, r4n = r4; float vvn = vv;
;         if (step + 1 < 16) {
;           const float* sp = bp + (step + 1) * 336;
;           w4n = *(const float4*)(sp + ks * 4);
;           kk4n = *(const float4*)(sp + 64 + ks * 4);
;           ka4n = *(const float4*)(sp + 128 + ks * 4);
;           kp4n = *(const float4*)(sp + 192 + ks * 4);
;           r4n = *(const float4*)(sp + 256 + ks * 4);
;           vvn = sp[320 + rowl];
;         }
;         const f2 kka = {kk4.x, kk4.y}, kkb = {kk4.z, kk4.w}, wa = {w4.x, w4.y}, wb = {w4.z, w4.w};
;         const f2 kaa = {ka4.x, ka4.y}, kab = {ka4.z, ka4.w}, kpa = {kp4.x, kp4.y}, kpb = {kp4.z, kp4.w};
;         const f2 ra = {r4.x, r4.y}, rb = {r4.z, r4.w};
;         const f2 d2 = Sa * kka + Sb * kkb;
;         float d = d2.x + d2.y;
;         const f2 ta = Sa * wa + kpa * vv, tb = Sb * wb + kpb * vv;
;         d = dpp_add<0xB1>(d); yp = dpp_add<0xB1>(yp);
;         d = dpp_add<0x4E>(d); yp = dpp_add<0x4E>(yp);
;         d = dpp_add<0x141>(d); yp = dpp_add<0x141>(yp);
;         d = dpp_add<0x140>(d); yp = dpp_add<0x140>(yp);
;         if (step > 0) yreg = (ks == step - 1) ? yp : yreg;
;         Sa = ta - kaa * d; Sb = tb - kab * d;
;         const f2 y2 = Sa * ra + Sb * rb;
;         yp = y2.x + y2.y;
;         w4 = w4n; kk4 = kk4n; ka4 = ka4n; kp4 = kp4n; r4 = r4n; vv = vvn;
;       }
;       yp = reduce16(yp);
;       yreg = (ks == 15) ? yp : yreg;
;       S0 = Sa.x; S1 = Sa.y; S2 = Sb.x; S3 = Sb.y;
;       yb[ks * 16 + rowl] = yreg;
	v_pk_fma_f32 v[14:15], v[26:27], v[0:1], v[14:15] op_sel_hi:[1,0,1]
	v_pk_fma_f32 v[16:17], v[28:29], v[0:1], v[16:17] op_sel_hi:[1,0,1]
	v_add_f32_dpp v0, v18, v18 quad_perm:[1,0,3,2] row_mask:0xf bank_mask:0xf bound_ctrl:1
	v_pk_mul_f32 v[34:35], v[52:53], v[66:67]
	s_nop 0
	v_add_f32_dpp v0, v0, v0 quad_perm:[2,3,0,1] row_mask:0xf bank_mask:0xf bound_ctrl:1
	v_pk_fma_f32 v[34:35], v[50:51], v[64:65], v[34:35]
	s_nop 0
	v_add_f32_dpp v0, v0, v0 row_half_mirror row_mask:0xf bank_mask:0xf bound_ctrl:1
	v_add_f32_e32 v81, v34, v35
	ds_write_b32 v99, v81 offset:11264
	ds_read_b128 v[34:37], v79 offset:17472
	ds_read_b128 v[38:41], v79 offset:17728
	ds_read_b128 v[42:45], v79 offset:17984
	ds_read_b128 v[46:49], v79 offset:18240
	ds_read_b128 v[50:53], v79 offset:18496
	ds_read_b32 v68, v78 offset:18752
	v_add_f32_dpp v0, v0, v0 row_mirror row_mask:0xf bank_mask:0xf bound_ctrl:1
	v_pk_fma_f32 v[64:65], v[22:23], v[0:1], v[14:15] op_sel_hi:[1,0,1] neg_lo:[1,0,0] neg_hi:[1,0,0]
	v_pk_fma_f32 v[66:67], v[24:25], v[0:1], v[16:17] op_sel_hi:[1,0,1] neg_lo:[1,0,0] neg_hi:[1,0,0]
	s_waitcnt lgkmcnt(4)
	v_pk_mul_f32 v[38:39], v[38:39], v[64:65]
	v_pk_mul_f32 v[14:15], v[32:33], v[66:67]
	v_pk_fma_f32 v[38:39], v[40:41], v[66:67], v[38:39]
	v_pk_fma_f32 v[14:15], v[30:31], v[64:65], v[14:15]
	v_add_f32_e32 v81, v14, v15
	ds_write_b32 v99, v81 offset:12288
	v_add_f32_e32 v38, v38, v39
	s_nop 1
	v_add_f32_dpp v38, v38, v38 quad_perm:[1,0,3,2] row_mask:0xf bank_mask:0xf bound_ctrl:1
	s_nop 1
	v_add_f32_dpp v38, v38, v38 quad_perm:[2,3,0,1] row_mask:0xf bank_mask:0xf bound_ctrl:1
	v_pk_mul_f32 v[34:35], v[34:35], v[64:65]
	s_nop 0
	v_add_f32_dpp v38, v38, v38 row_half_mirror row_mask:0xf bank_mask:0xf bound_ctrl:1
	s_waitcnt lgkmcnt(0)
	v_pk_fma_f32 v[34:35], v[46:47], v[68:69], v[34:35] op_sel_hi:[1,0,1]
	v_pk_mul_f32 v[36:37], v[36:37], v[66:67]
	v_add_f32_dpp v38, v38, v38 row_mirror row_mask:0xf bank_mask:0xf bound_ctrl:1
	ds_read_b128 v[22:25], v79 offset:18816
	ds_read_b128 v[30:33], v79 offset:19072
	ds_read_b128 v[14:17], v79 offset:19328
	ds_read_b128 v[26:29], v79 offset:19584
	ds_read_b128 v[18:21], v79 offset:19840
	ds_read_b32 v0, v78 offset:20096
	v_pk_fma_f32 v[36:37], v[48:49], v[68:69], v[36:37] op_sel_hi:[1,0,1]
	v_pk_fma_f32 v[66:67], v[42:43], v[38:39], v[34:35] op_sel_hi:[1,0,1] neg_lo:[1,0,0] neg_hi:[1,0,0]
	v_pk_fma_f32 v[64:65], v[44:45], v[38:39], v[36:37] op_sel_hi:[1,0,1] neg_lo:[1,0,0] neg_hi:[1,0,0]
	s_waitcnt lgkmcnt(4)
	v_pk_mul_f32 v[30:31], v[30:31], v[66:67]
	v_pk_mul_f32 v[22:23], v[22:23], v[66:67]
	v_pk_fma_f32 v[30:31], v[32:33], v[64:65], v[30:31]
	v_pk_mul_f32 v[34:35], v[52:53], v[64:65]
	v_add_f32_e32 v30, v30, v31
	s_waitcnt lgkmcnt(0)
	v_pk_fma_f32 v[22:23], v[26:27], v[0:1], v[22:23] op_sel_hi:[1,0,1]
	v_pk_fma_f32 v[34:35], v[50:51], v[66:67], v[34:35]
	v_add_f32_dpp v30, v30, v30 quad_perm:[1,0,3,2] row_mask:0xf bank_mask:0xf bound_ctrl:1
	v_add_f32_e32 v81, v34, v35
	ds_write_b32 v99, v81 offset:13312
	v_add_f32_dpp v30, v30, v30 quad_perm:[2,3,0,1] row_mask:0xf bank_mask:0xf bound_ctrl:1
	ds_read_b128 v[42:45], v79 offset:20160
	ds_read_b128 v[50:53], v79 offset:20416
	ds_read_b128 v[34:37], v79 offset:20672
	ds_read_b128 v[46:49], v79 offset:20928
	ds_read_b128 v[38:41], v79 offset:21184
	ds_read_b32 v68, v78 offset:21440
	v_add_f32_dpp v30, v30, v30 row_half_mirror row_mask:0xf bank_mask:0xf bound_ctrl:1
	s_nop 0
	s_nop 0
	v_add_f32_dpp v26, v30, v30 row_mirror row_mask:0xf bank_mask:0xf bound_ctrl:1
	v_pk_fma_f32 v[14:15], v[14:15], v[26:27], v[22:23] op_sel_hi:[1,0,1] neg_lo:[1,0,0] neg_hi:[1,0,0]
	v_pk_mul_f32 v[22:23], v[24:25], v[64:65]
	v_pk_fma_f32 v[22:23], v[28:29], v[0:1], v[22:23] op_sel_hi:[1,0,1]
	s_nop 0
	v_pk_fma_f32 v[16:17], v[16:17], v[26:27], v[22:23] op_sel_hi:[1,0,1] neg_lo:[1,0,0] neg_hi:[1,0,0]
	s_nop 0
	v_pk_mul_f32 v[20:21], v[20:21], v[16:17]
	s_nop 0
	v_pk_fma_f32 v[18:19], v[18:19], v[14:15], v[20:21]
	s_nop 0
	v_add_f32_e32 v0, v18, v19
	ds_write_b32 v99, v0 offset:14336
	s_waitcnt lgkmcnt(4)
	v_pk_mul_f32 v[18:19], v[50:51], v[14:15]
	v_pk_fma_f32 v[18:19], v[52:53], v[16:17], v[18:19]
	v_pk_mul_f32 v[16:17], v[44:45], v[16:17]
	v_add_f32_e32 v18, v18, v19
	v_pk_mul_f32 v[14:15], v[42:43], v[14:15]
	s_nop 0
	v_add_f32_dpp v18, v18, v18 quad_perm:[1,0,3,2] row_mask:0xf bank_mask:0xf bound_ctrl:1
	s_waitcnt lgkmcnt(0)
	v_pk_fma_f32 v[16:17], v[48:49], v[68:69], v[16:17] op_sel_hi:[1,0,1]
	v_add_f32_dpp v18, v18, v18 quad_perm:[2,3,0,1] row_mask:0xf bank_mask:0xf bound_ctrl:1
	v_pk_fma_f32 v[14:15], v[46:47], v[68:69], v[14:15] op_sel_hi:[1,0,1]
	s_nop 0
	v_add_f32_dpp v18, v18, v18 row_half_mirror row_mask:0xf bank_mask:0xf bound_ctrl:1
	s_nop 1
	v_add_f32_dpp v0, v18, v18 row_mirror row_mask:0xf bank_mask:0xf bound_ctrl:1
	v_pk_fma_f32 v[16:17], v[36:37], v[0:1], v[16:17] op_sel_hi:[1,0,1] neg_lo:[1,0,0] neg_hi:[1,0,0]
	v_pk_fma_f32 v[14:15], v[34:35], v[0:1], v[14:15] op_sel_hi:[1,0,1] neg_lo:[1,0,0] neg_hi:[1,0,0]
	v_pk_mul_f32 v[18:19], v[40:41], v[16:17]
	s_nop 0
	v_pk_fma_f32 v[18:19], v[38:39], v[14:15], v[18:19]
	s_nop 0
	v_add_f32_e32 v0, v18, v19
	ds_write_b32 v99, v0 offset:15360
	v_add3_u32 v18, s63, v75, v76
	s_nop 0
	s_nop 1
	s_nop 1
	s_nop 1

; DI void scan_block(float* ldsf, const u16* __restrict__ R, const u16* __restrict__ KP, const u16* __restrict__ KK, const u16* __restrict__ KKA,
;                    const u16* __restrict__ V, const float* __restrict__ Wd, float* __restrict__ Y, int blk, int wid_k) {
;     ...
;     __syncthreads();
;     if (tid < 256) {
;       const int step = tid >> 4, row = tid & 15;
;       Y[(tb + (size_t)c * 16 + step) * 256 + hc + rq * 16 + row] = yb[tid];
;     }
.LBB0_1296:
	s_waitcnt lgkmcnt(0)
	s_barrier
	s_andn1_saveexec_b64 s[60:61], s[2:3]
	s_cbranch_execz .LBB0_1281
	s_lshl_b32 s67, s66, 14
	s_add_i32 s67, s67, 0xfc00
	v_lshl_add_u32 v18, v69, 2, s67
	ds_read_b32 v100, v18
	ds_read_b32 v101, v18 offset:1024
	ds_read_b32 v102, v18 offset:2048
	ds_read_b32 v103, v18 offset:3072
	ds_read_b32 v104, v18 offset:4096
	ds_read_b32 v105, v18 offset:5120
	ds_read_b32 v106, v18 offset:6144
	ds_read_b32 v107, v18 offset:7168
	ds_read_b32 v108, v18 offset:8192
	ds_read_b32 v109, v18 offset:9216
	ds_read_b32 v110, v18 offset:10240
	ds_read_b32 v111, v18 offset:11264
	ds_read_b32 v112, v18 offset:12288
	ds_read_b32 v113, v18 offset:13312
	ds_read_b32 v114, v18 offset:14336
	ds_read_b32 v115, v18 offset:15360
	s_waitcnt lgkmcnt(0)
; DI float reduce16(float v) {
;   v = dpp_add<0xB1>(v);
;   v = dpp_add<0x4E>(v);
;   v = dpp_add<0x141>(v);
;   v = dpp_add<0x140>(v);
;   return v;
; }
; DI void scan_block(float* ldsf, const u16* __restrict__ R, const u16* __restrict__ KP, const u16* __restrict__ KK, const u16* __restrict__ KKA,
;                    const u16* __restrict__ V, const float* __restrict__ Wd, float* __restrict__ Y, int blk, int wid_k) {
;     ...
;         if (step > 0) yreg = (ks == step - 1) ? yp : yreg;
;         Sa = ta - kaa * d; Sb = tb - kab * d;
;         const f2 y2 = Sa * ra + Sb * rb;
;         yp = y2.x + y2.y;
;         w4 = w4n; kk4 = kk4n; ka4 = ka4n; kp4 = kp4n; r4 = r4n; vv = vvn;
;       }
;       yp = reduce16(yp);
;       yreg = (ks == 15) ? yp : yreg;
;       S0 = Sa.x; S1 = Sa.y; S2 = Sb.x; S3 = Sb.y;
;       yb[ks * 16 + rowl] = yreg;
;     }
;     if (c + 1 < SEQ / 16) SCAN_COMMIT(cur ^ 1);
;     __syncthreads();
;     if (tid < 256) {
;       const int step = tid >> 4, row = tid & 15;
;       Y[(tb + (size_t)c * 16 + step) * 256 + hc + rq * 16 + row] = yb[tid];
;     }
	v_add_f32_dpp v100, v100, v100 quad_perm:[1,0,3,2] row_mask:0xf bank_mask:0xf bound_ctrl:1
	v_add_f32_dpp v101, v101, v101 quad_perm:[1,0,3,2] row_mask:0xf bank_mask:0xf bound_ctrl:1
	v_add_f32_dpp v102, v102, v102 quad_perm:[1,0,3,2] row_mask:0xf bank_mask:0xf bound_ctrl:1
	v_add_f32_dpp v103, v103, v103 quad_perm:[1,0,3,2] row_mask:0xf bank_mask:0xf bound_ctrl:1
	v_add_f32_dpp v104, v104, v104 quad_perm:[1,0,3,2] row_mask:0xf bank_mask:0xf bound_ctrl:1
	v_add_f32_dpp v105, v105, v105 quad_perm:[1,0,3,2] row_mask:0xf bank_mask:0xf bound_ctrl:1
	v_add_f32_dpp v106, v106, v106 quad_perm:[1,0,3,2] row_mask:0xf bank_mask:0xf bound_ctrl:1
	v_add_f32_dpp v107, v107, v107 quad_perm:[1,0,3,2] row_mask:0xf bank_mask:0xf bound_ctrl:1
	v_add_f32_dpp v108, v108, v108 quad_perm:[1,0,3,2] row_mask:0xf bank_mask:0xf bound_ctrl:1
	v_add_f32_dpp v109, v109, v109 quad_perm:[1,0,3,2] row_mask:0xf bank_mask:0xf bound_ctrl:1
	v_add_f32_dpp v110, v110, v110 quad_perm:[1,0,3,2] row_mask:0xf bank_mask:0xf bound_ctrl:1
	v_add_f32_dpp v111, v111, v111 quad_perm:[1,0,3,2] row_mask:0xf bank_mask:0xf bound_ctrl:1
	v_add_f32_dpp v112, v112, v112 quad_perm:[1,0,3,2] row_mask:0xf bank_mask:0xf bound_ctrl:1
	v_add_f32_dpp v113, v113, v113 quad_perm:[1,0,3,2] row_mask:0xf bank_mask:0xf bound_ctrl:1
	v_add_f32_dpp v114, v114, v114 quad_perm:[1,0,3,2] row_mask:0xf bank_mask:0xf bound_ctrl:1
	v_add_f32_dpp v115, v115, v115 quad_perm:[1,0,3,2] row_mask:0xf bank_mask:0xf bound_ctrl:1
	v_add_f32_dpp v100, v100, v100 quad_perm:[2,3,0,1] row_mask:0xf bank_mask:0xf bound_ctrl:1
	v_add_f32_dpp v101, v101, v101 quad_perm:[2,3,0,1] row_mask:0xf bank_mask:0xf bound_ctrl:1
	v_add_f32_dpp v102, v102, v102 quad_perm:[2,3,0,1] row_mask:0xf bank_mask:0xf bound_ctrl:1
	v_add_f32_dpp v103, v103, v103 quad_perm:[2,3,0,1] row_mask:0xf bank_mask:0xf bound_ctrl:1
	v_add_f32_dpp v104, v104, v104 quad_perm:[2,3,0,1] row_mask:0xf bank_mask:0xf bound_ctrl:1
	v_add_f32_dpp v105, v105, v105 quad_perm:[2,3,0,1] row_mask:0xf bank_mask:0xf bound_ctrl:1
	v_add_f32_dpp v106, v106, v106 quad_perm:[2,3,0,1] row_mask:0xf bank_mask:0xf bound_ctrl:1
	v_add_f32_dpp v107, v107, v107 quad_perm:[2,3,0,1] row_mask:0xf bank_mask:0xf bound_ctrl:1
	v_add_f32_dpp v108, v108, v108 quad_perm:[2,3,0,1] row_mask:0xf bank_mask:0xf bound_ctrl:1
	v_add_f32_dpp v109, v109, v109 quad_perm:[2,3,0,1] row_mask:0xf bank_mask:0xf bound_ctrl:1
	v_add_f32_dpp v110, v110, v110 quad_perm:[2,3,0,1] row_mask:0xf bank_mask:0xf bound_ctrl:1
	v_add_f32_dpp v111, v111, v111 quad_perm:[2,3,0,1] row_mask:0xf bank_mask:0xf bound_ctrl:1
	v_add_f32_dpp v112, v112, v112 quad_perm:[2,3,0,1] row_mask:0xf bank_mask:0xf bound_ctrl:1
	v_add_f32_dpp v113, v113, v113 quad_perm:[2,3,0,1] row_mask:0xf bank_mask:0xf bound_ctrl:1
	v_add_f32_dpp v114, v114, v114 quad_perm:[2,3,0,1] row_mask:0xf bank_mask:0xf bound_ctrl:1
	v_add_f32_dpp v115, v115, v115 quad_perm:[2,3,0,1] row_mask:0xf bank_mask:0xf bound_ctrl:1
	v_add_f32_dpp v100, v100, v100 row_half_mirror row_mask:0xf bank_mask:0xf bound_ctrl:1
	v_add_f32_dpp v101, v101, v101 row_half_mirror row_mask:0xf bank_mask:0xf bound_ctrl:1
	v_add_f32_dpp v102, v102, v102 row_half_mirror row_mask:0xf bank_mask:0xf bound_ctrl:1
	v_add_f32_dpp v103, v103, v103 row_half_mirror row_mask:0xf bank_mask:0xf bound_ctrl:1
	v_add_f32_dpp v104, v104, v104 row_half_mirror row_mask:0xf bank_mask:0xf bound_ctrl:1
	v_add_f32_dpp v105, v105, v105 row_half_mirror row_mask:0xf bank_mask:0xf bound_ctrl:1
	v_add_f32_dpp v106, v106, v106 row_half_mirror row_mask:0xf bank_mask:0xf bound_ctrl:1
	v_add_f32_dpp v107, v107, v107 row_half_mirror row_mask:0xf bank_mask:0xf bound_ctrl:1
	v_add_f32_dpp v108, v108, v108 row_half_mirror row_mask:0xf bank_mask:0xf bound_ctrl:1
	v_add_f32_dpp v109, v109, v109 row_half_mirror row_mask:0xf bank_mask:0xf bound_ctrl:1
	v_add_f32_dpp v110, v110, v110 row_half_mirror row_mask:0xf bank_mask:0xf bound_ctrl:1
	v_add_f32_dpp v111, v111, v111 row_half_mirror row_mask:0xf bank_mask:0xf bound_ctrl:1
	v_add_f32_dpp v112, v112, v112 row_half_mirror row_mask:0xf bank_mask:0xf bound_ctrl:1
	v_add_f32_dpp v113, v113, v113 row_half_mirror row_mask:0xf bank_mask:0xf bound_ctrl:1
	v_add_f32_dpp v114, v114, v114 row_half_mirror row_mask:0xf bank_mask:0xf bound_ctrl:1
	v_add_f32_dpp v115, v115, v115 row_half_mirror row_mask:0xf bank_mask:0xf bound_ctrl:1
	v_add_f32_dpp v100, v100, v100 row_mirror row_mask:0xf bank_mask:0xf bound_ctrl:1
	v_add_f32_dpp v101, v101, v101 row_mirror row_mask:0xf bank_mask:0xf bound_ctrl:1
	v_add_f32_dpp v102, v102, v102 row_mirror row_mask:0xf bank_mask:0xf bound_ctrl:1
	v_add_f32_dpp v103, v103, v103 row_mirror row_mask:0xf bank_mask:0xf bound_ctrl:1
	v_add_f32_dpp v104, v104, v104 row_mirror row_mask:0xf bank_mask:0xf bound_ctrl:1
	v_add_f32_dpp v105, v105, v105 row_mirror row_mask:0xf bank_mask:0xf bound_ctrl:1
	v_add_f32_dpp v106, v106, v106 row_mirror row_mask:0xf bank_mask:0xf bound_ctrl:1
	v_add_f32_dpp v107, v107, v107 row_mirror row_mask:0xf bank_mask:0xf bound_ctrl:1
	v_add_f32_dpp v108, v108, v108 row_mirror row_mask:0xf bank_mask:0xf bound_ctrl:1
	v_add_f32_dpp v109, v109, v109 row_mirror row_mask:0xf bank_mask:0xf bound_ctrl:1
	v_add_f32_dpp v110, v110, v110 row_mirror row_mask:0xf bank_mask:0xf bound_ctrl:1
	v_add_f32_dpp v111, v111, v111 row_mirror row_mask:0xf bank_mask:0xf bound_ctrl:1
	v_add_f32_dpp v112, v112, v112 row_mirror row_mask:0xf bank_mask:0xf bound_ctrl:1
	v_add_f32_dpp v113, v113, v113 row_mirror row_mask:0xf bank_mask:0xf bound_ctrl:1
	v_add_f32_dpp v114, v114, v114 row_mirror row_mask:0xf bank_mask:0xf bound_ctrl:1
	v_add_f32_dpp v115, v115, v115 row_mirror row_mask:0xf bank_mask:0xf bound_ctrl:1
	v_cndmask_b32_e64 v100, v100, v101, s[12:13]
	v_cndmask_b32_e64 v100, v100, v102, s[14:15]
	v_cndmask_b32_e64 v100, v100, v103, s[16:17]
	v_cndmask_b32_e64 v100, v100, v104, s[18:19]
	v_cndmask_b32_e64 v100, v100, v105, s[20:21]
	v_cndmask_b32_e64 v100, v100, v106, s[22:23]
	v_cndmask_b32_e64 v100, v100, v107, s[24:25]
	v_cndmask_b32_e64 v100, v100, v108, s[26:27]
	v_cndmask_b32_e64 v100, v100, v109, s[28:29]
	v_cndmask_b32_e64 v100, v100, v110, s[30:31]
	v_cndmask_b32_e64 v100, v100, v111, s[34:35]
	v_cndmask_b32_e64 v100, v100, v112, s[36:37]
	v_cndmask_b32_e64 v100, v100, v113, s[38:39]
	v_cndmask_b32_e64 v100, v100, v114, s[40:41]
	v_cndmask_b32_e64 v100, v100, v115, s[8:9]
	v_lshl_add_u64 v[18:19], s[48:49], 0, v[56:57]
	global_store_dword v[18:19], v100, off
	s_branch .LBB0_1281

; DI unsigned pack2(float a, float b) { f32v2 v = {a, b}; bf16v2 r = __builtin_convertvector(v, bf16v2); return __builtin_bit_cast(unsigned, r); }
; #define MFMA32(a, b, c) __builtin_amdgcn_mfma_f32_32x32x16_bf16((a), (b), (c), 0, 0, 0)
; template <int DK, int DV, bool BIAS>
; DI void attn_item(u16* lds, const u16* __restrict__ Q, const u16* __restrict__ Kg, const u16* __restrict__ VT,
;                   const float* __restrict__ cum, u16* __restrict__ O, int ldo, int bh, int qb, int wid_k) {
;     ...
;       float mx = st[0];
; #pragma unroll
;       for (int i = 1; i < 16; ++i) mx = fmaxf(mx, st[i]);
;       { auto r_ = __builtin_amdgcn_permlane32_swap(__float_as_uint(mx), __float_as_uint(mx), false, false); mx = fmaxf(__uint_as_float(r_[0]), __uint_as_float(r_[1])); }
;       const float mnew = fmaxf(mrun, mx);
;       const float alpha = __builtin_amdgcn_exp2f(mrun - mnew);
;       const bool resc = __builtin_amdgcn_ballot_w64(mnew > mrun) != 0ull;
;       mrun = mnew;
;       float ps = 0.f;
; #pragma unroll
;       for (int i = 0; i < 16; ++i) { st[i] = __builtin_amdgcn_exp2f(st[i] - mnew); ps += st[i]; }
;       lrun = lrun * alpha + ps;
;       if (resc) {
; #pragma unroll
;         for (int mb = 0; mb < NMB; ++mb)
; #pragma unroll
;           for (int i = 0; i < 16; ++i) o[mb][i] *= alpha;
;       }
;       bf16x8 pf[2];
; #pragma unroll
;       for (int s = 0; s < 2; ++s) {
;         uint4 pk;
;         pk.x = pack2(st[8 * s + 0], st[8 * s + 1]); pk.y = pack2(st[8 * s + 2], st[8 * s + 3]);
;         pk.z = pack2(st[8 * s + 4], st[8 * s + 5]); pk.w = pack2(st[8 * s + 6], st[8 * s + 7]);
;         pf[s] = __builtin_bit_cast(bf16x8, pk);
;       }
; #pragma unroll
;       for (int mb = 0; mb < NMB; ++mb)
; #pragma unroll
;         for (int s = 0; s < 2; ++s) {
;           const u16* vpp = ldsV + (mb * 32 + l31) * 72 + kh * 32 + 16 * s + 4 * h2;
;           const s16x4 lo = *(const s16x4*)(vpp);
;           const s16x4 hi = *(const s16x4*)(vpp + 8);
;           const bf16x8 vf = __builtin_shufflevector(lo, hi, 0, 1, 2, 3, 4, 5, 6, 7);
;           o[mb] = MFMA32(vf, pf[s], o[mb]);
;         }
.LBB0_1355:
	v_sub_f32_e32 v2, v80, v7
	v_exp_f32_e32 v2, v2
	v_sub_f32_e32 v4, v81, v7
	v_exp_f32_e32 v4, v4
	v_sub_f32_e32 v5, v82, v7
	v_exp_f32_e32 v5, v5
	v_sub_f32_e32 v8, v83, v7
	v_exp_f32_e32 v9, v8
	v_sub_f32_e32 v8, v84, v7
	v_add_f32_e32 v3, 0, v2
	v_exp_f32_e32 v10, v8
	v_sub_f32_e32 v8, v85, v7
	v_add_f32_e32 v3, v4, v3
	v_exp_f32_e32 v11, v8
	v_sub_f32_e32 v8, v86, v7
	v_add_f32_e32 v3, v5, v3
	v_exp_f32_e32 v12, v8
	v_sub_f32_e32 v8, v87, v7
	v_add_f32_e32 v3, v9, v3
	v_exp_f32_e32 v13, v8
	v_sub_f32_e32 v8, v88, v7
	v_add_f32_e32 v3, v10, v3
	v_exp_f32_e32 v14, v8
	v_sub_f32_e32 v8, v89, v7
	v_add_f32_e32 v3, v11, v3
	v_exp_f32_e32 v15, v8
	v_sub_f32_e32 v8, v90, v7
	v_add_f32_e32 v3, v12, v3
	v_exp_f32_e32 v80, v8
	v_sub_f32_e32 v8, v91, v7
	v_add_f32_e32 v3, v13, v3
	v_exp_f32_e32 v81, v8
	v_sub_f32_e32 v8, v92, v7
	v_add_f32_e32 v3, v14, v3
	v_exp_f32_e32 v82, v8
	v_sub_f32_e32 v8, v93, v7
	v_add_f32_e32 v3, v15, v3
	v_exp_f32_e32 v83, v8
	v_sub_f32_e32 v8, v94, v7
	v_add_f32_e32 v3, v80, v3
	v_exp_f32_e32 v84, v8
	v_sub_f32_e32 v8, v95, v7
	v_add_f32_e32 v3, v81, v3
	v_exp_f32_e32 v85, v8
	v_add_f32_e32 v3, v82, v3
	v_add_f32_e32 v3, v83, v3
	v_add_f32_e32 v3, v84, v3
	v_add_f32_e32 v86, v85, v3
	v_fmac_f32_e32 v86, v205, v0
	v_add_u32_e32 v0, v6, v204
	v_add_u32_e32 v6, 0x6000, v0
	v_cvt_pk_bf16_f32 v8, v2, v4
	v_cvt_pk_bf16_f32 v10, v10, v11
	v_cvt_pk_bf16_f32 v11, v12, v13
	v_cvt_pk_bf16_f32 v2, v14, v15
	v_cvt_pk_bf16_f32 v3, v80, v81
	v_cvt_pk_bf16_f32 v4, v82, v83
	v_cvt_pk_bf16_f32 v9, v5, v9
	v_add_u32_e32 v6, 0x7000, v0
	v_cvt_pk_bf16_f32 v5, v84, v85
	s_waitcnt lgkmcnt(0)
	v_mfma_f32_32x32x16_bf16 v[64:79], v[232:235], v[8:11], v[64:79]
	v_mov_b32_e32 v206, v7
	v_mov_b32_e32 v205, v86
	v_mfma_f32_32x32x16_bf16 v[48:63], v[240:243], v[8:11], v[48:63]
	v_add_u32_e32 v6, 0x8800, v0
	v_add_u32_e32 v0, 0x9800, v0
	v_mfma_f32_32x32x16_bf16 v[48:63], v[244:247], v[2:5], v[48:63]
	v_mfma_f32_32x32x16_bf16 v[32:47], v[248:251], v[8:11], v[32:47]
	v_mfma_f32_32x32x16_bf16 v[32:47], v[208:211], v[2:5], v[32:47]
	v_mfma_f32_32x32x16_bf16 v[16:31], v[212:215], v[8:11], v[16:31]
	v_mfma_f32_32x32x16_bf16 v[64:79], v[236:239], v[2:5], v[64:79]
	v_mfma_f32_32x32x16_bf16 v[16:31], v[216:219], v[2:5], v[16:31]

; #define MFMA32(a, b, c) __builtin_amdgcn_mfma_f32_32x32x16_bf16((a), (b), (c), 0, 0, 0)
; template <int DK, int DV, bool BIAS>
; DI void attn_item(u16* lds, const u16* __restrict__ Q, const u16* __restrict__ Kg, const u16* __restrict__ VT,
;                   const float* __restrict__ cum, u16* __restrict__ O, int ldo, int bh, int qb, int wid_k) {
;     ...
;     const u16* ldsK = lds + (kt & 1) * TILE_U16_; const u16* ldsV = ldsK + 64 * KSTR; const float* ldsC = (const float*)(ldsV + DV * 72);
; #pragma unroll
;     for (int kh = 0; kh < 2; ++kh) {
;       const int kb = k0 + kh * 32;
;       if (kb > wq0 + 31) continue;
;       f32x16 st;
; #pragma unroll
;       for (int i = 0; i < 16; ++i) st[i] = 0.f;
; #pragma unroll
;       for (int ks = 0; ks < NKS; ++ks) {
;         const bf16x8 kf = *(const bf16x8*)(ldsK + (kh * 32 + l31) * KSTR + ks * 16 + h2 * 8);
;         st = MFMA32(kf, qf[ks], st);
;       }
;       if (BIAS) {
; #pragma unroll
;         for (int g = 0; g < 4; ++g) {
;           const float4 ck = *(const float4*)(ldsC + kh * 32 + 8 * g + 4 * h2);
;           st[4 * g + 0] += cq - ck.x; st[4 * g + 1] += cq - ck.y; st[4 * g + 2] += cq - ck.z; st[4 * g + 3] += cq - ck.w;
;         }
;       }
;       if (kb + 31 > wq0) {
; #pragma unroll
;         for (int i = 0; i < 16; ++i) {
;           const int key = kb + (i & 3) + 8 * (i >> 2) + 4 * h2;
;           if (key > qrow) st[i] = -1e30f;
;         }
;       }
;     ...
;           const u16* vpp = ldsV + (mb * 32 + l31) * 72 + kh * 32 + 16 * s + 4 * h2;
;           const s16x4 lo = *(const s16x4*)(vpp);
;           const s16x4 hi = *(const s16x4*)(vpp + 8);
;           const bf16x8 vf = __builtin_shufflevector(lo, hi, 0, 1, 2, 3, 4, 5, 6, 7);
.LBB0_1361:
	s_or_b64 exec, exec, s[40:41]
	s_bitcmp1_b32 s60, 0
	s_cselect_b32 s40, 0xad00, 0
	s_add_i32 s40, s40, 0
	v_lshl_add_u32 v0, v165, 1, s40
	v_add_u32_e32 v6, s40, v165
	v_cmp_le_i32_e32 vcc, s72, v202
	v_add_u32_e32 v7, v0, v203
	s_and_saveexec_b64 s[40:41], vcc
	s_cbranch_execz .LBB0_1367
	ds_read_b128 v[232:235], v7
	ds_read_b128 v[236:239], v7 offset:32
	ds_read_b128 v[240:243], v7 offset:64
	ds_read_b128 v[244:247], v7 offset:96
	ds_read_b128 v[248:251], v7 offset:128
	ds_read_b128 v[208:211], v7 offset:160
	s_add_i32 s48, s72, 31
	v_cmp_gt_i32_e32 vcc, s48, v193
	s_waitcnt lgkmcnt(5)
	v_mfma_f32_32x32x16_bf16 v[80:95], v[232:235], v[96:99], 0
	ds_read_b128 v[232:235], v7 offset:192
	s_waitcnt lgkmcnt(5)
	v_mfma_f32_32x32x16_bf16 v[80:95], v[236:239], v[100:103], v[80:95]
	ds_read_b128 v[236:239], v7 offset:224
	s_waitcnt lgkmcnt(5)
	v_mfma_f32_32x32x16_bf16 v[80:95], v[240:243], v[104:107], v[80:95]
	ds_read_b128 v[240:243], v7 offset:256
	s_waitcnt lgkmcnt(5)
	v_mfma_f32_32x32x16_bf16 v[80:95], v[244:247], v[108:111], v[80:95]
	ds_read_b128 v[244:247], v7 offset:288
	s_waitcnt lgkmcnt(5)
	v_mfma_f32_32x32x16_bf16 v[80:95], v[248:251], v[112:115], v[80:95]
	ds_read_b128 v[248:251], v7 offset:320
	s_waitcnt lgkmcnt(5)
	v_mfma_f32_32x32x16_bf16 v[80:95], v[208:211], v[116:119], v[80:95]
	ds_read_b128 v[208:211], v7 offset:352
	s_waitcnt lgkmcnt(5)
	v_mfma_f32_32x32x16_bf16 v[80:95], v[232:235], v[120:123], v[80:95]
	s_waitcnt lgkmcnt(4)
	v_mfma_f32_32x32x16_bf16 v[80:95], v[236:239], v[124:127], v[80:95]
	s_waitcnt lgkmcnt(3)
	v_mfma_f32_32x32x16_bf16 v[80:95], v[240:243], v[128:131], v[80:95]
	s_waitcnt lgkmcnt(2)
	v_mfma_f32_32x32x16_bf16 v[80:95], v[244:247], v[132:135], v[80:95]
	s_waitcnt lgkmcnt(1)
	v_mfma_f32_32x32x16_bf16 v[80:95], v[248:251], v[136:139], v[80:95]
	s_waitcnt lgkmcnt(0)
	v_mfma_f32_32x32x16_bf16 v[80:95], v[208:211], v[140:143], v[80:95]
	v_add_u32_e32 v221, v6, v204
	v_add_u32_e32 v222, 0x6000, v221
	v_add_u32_e32 v223, 0x7000, v221
	v_add_u32_e32 v224, 0x8800, v221
	v_add_u32_e32 v225, 0x9800, v221
	ds_read2_b64 v[232:235], v222 offset0:128 offset1:130
	ds_read2_b64 v[236:239], v222 offset0:132 offset1:134
	ds_read2_b64 v[240:243], v223 offset0:192 offset1:194
	ds_read2_b64 v[244:247], v223 offset0:196 offset1:198
	ds_read2_b64 v[248:251], v224 offset1:2
	ds_read2_b64 v[208:211], v224 offset0:4 offset1:6
	ds_read2_b64 v[212:215], v225 offset0:64 offset1:66
	ds_read2_b64 v[216:219], v225 offset0:68 offset1:70
	s_and_saveexec_b64 s[48:49], vcc
	s_cbranch_execz .LBB0_1364
	v_add_u32_e32 v0, s72, v196
	v_cmp_lt_i32_e32 vcc, v0, v166
	v_add_u32_e32 v2, 2, v0
	s_nop 6
	v_cndmask_b32_e32 v81, v229, v81, vcc
	v_cmp_le_i32_e32 vcc, v0, v166
	s_nop 1
	v_cndmask_b32_e32 v80, v229, v80, vcc
	v_cmp_le_i32_e32 vcc, v2, v166
	v_add_u32_e32 v2, 3, v0
	s_nop 0
	v_cndmask_b32_e32 v82, v229, v82, vcc
	v_cmp_le_i32_e32 vcc, v2, v166
	v_add_u32_e32 v2, 8, v0
	s_nop 0
	v_cndmask_b32_e32 v83, v229, v83, vcc
	v_cmp_le_i32_e32 vcc, v2, v166
	v_add_u32_e32 v2, 9, v0
	s_nop 0
	v_cndmask_b32_e32 v84, v229, v84, vcc
	v_cmp_le_i32_e32 vcc, v2, v166
	v_add_u32_e32 v2, 10, v0
	s_nop 0
	v_cndmask_b32_e32 v85, v229, v85, vcc
	v_cmp_le_i32_e32 vcc, v2, v166
	v_add_u32_e32 v2, 11, v0
	s_nop 0
	v_cndmask_b32_e32 v86, v229, v86, vcc
	v_cmp_le_i32_e32 vcc, v2, v166
	v_add_u32_e32 v2, 16, v0
	s_nop 0
	v_cndmask_b32_e32 v87, v229, v87, vcc
	v_cmp_le_i32_e32 vcc, v2, v166
	v_add_u32_e32 v2, 17, v0
	s_nop 0
	v_cndmask_b32_e32 v88, v229, v88, vcc
	v_cmp_le_i32_e32 vcc, v2, v166
	v_add_u32_e32 v2, 18, v0
	s_nop 0
	v_cndmask_b32_e32 v89, v229, v89, vcc
	v_cmp_le_i32_e32 vcc, v2, v166
	v_add_u32_e32 v2, 19, v0
	s_nop 0
	v_cndmask_b32_e32 v90, v229, v90, vcc
	v_cmp_le_i32_e32 vcc, v2, v166
	v_add_u32_e32 v2, 24, v0
	s_nop 0
	v_cndmask_b32_e32 v91, v229, v91, vcc
	v_cmp_le_i32_e32 vcc, v2, v166
	v_add_u32_e32 v2, 25, v0
	s_nop 0
	v_cndmask_b32_e32 v92, v229, v92, vcc
	v_cmp_le_i32_e32 vcc, v2, v166
	v_add_u32_e32 v2, 26, v0
	v_add_u32_e32 v0, 27, v0
	v_cndmask_b32_e32 v93, v229, v93, vcc
	v_cmp_le_i32_e32 vcc, v2, v166
	s_nop 1
	v_cndmask_b32_e32 v94, v229, v94, vcc
	v_cmp_le_i32_e32 vcc, v0, v166
	s_nop 1
	v_cndmask_b32_e32 v95, v229, v95, vcc

; DI unsigned pack2(float a, float b) { f32v2 v = {a, b}; bf16v2 r = __builtin_convertvector(v, bf16v2); return __builtin_bit_cast(unsigned, r); }
; template <int DK, int DV, bool BIAS>
; DI void attn_item(u16* lds, const u16* __restrict__ Q, const u16* __restrict__ Kg, const u16* __restrict__ VT,
;                   const float* __restrict__ cum, u16* __restrict__ O, int ldo, int bh, int qb, int wid_k) {
;     ...
;       const int kb = k0 + kh * 32;
;       if (kb > wq0 + 31) continue;
;       f32x16 st;
; #pragma unroll
;       for (int i = 0; i < 16; ++i) st[i] = 0.f;
; #pragma unroll
;       for (int ks = 0; ks < NKS; ++ks) {
;         const bf16x8 kf = *(const bf16x8*)(ldsK + (kh * 32 + l31) * KSTR + ks * 16 + h2 * 8);
;         st = MFMA32(kf, qf[ks], st);
;       }
;       if (BIAS) {
; #pragma unroll
;         for (int g = 0; g < 4; ++g) {
;           const float4 ck = *(const float4*)(ldsC + kh * 32 + 8 * g + 4 * h2);
;           st[4 * g + 0] += cq - ck.x; st[4 * g + 1] += cq - ck.y; st[4 * g + 2] += cq - ck.z; st[4 * g + 3] += cq - ck.w;
;         }
;       }
;       if (kb + 31 > wq0) {
; #pragma unroll
;         for (int i = 0; i < 16; ++i) {
;           const int key = kb + (i & 3) + 8 * (i >> 2) + 4 * h2;
;           if (key > qrow) st[i] = -1e30f;
;     ...
;       for (int i = 0; i < 16; ++i) { st[i] = __builtin_amdgcn_exp2f(st[i] - mnew); ps += st[i]; }
;       lrun = lrun * alpha + ps;
;       if (resc) {
; #pragma unroll
;         for (int mb = 0; mb < NMB; ++mb)
; #pragma unroll
;           for (int i = 0; i < 16; ++i) o[mb][i] *= alpha;
;       }
;       bf16x8 pf[2];
; #pragma unroll
;       for (int s = 0; s < 2; ++s) {
;         uint4 pk;
;         pk.x = pack2(st[8 * s + 0], st[8 * s + 1]); pk.y = pack2(st[8 * s + 2], st[8 * s + 3]);
;         pk.z = pack2(st[8 * s + 4], st[8 * s + 5]); pk.w = pack2(st[8 * s + 6], st[8 * s + 7]);
;         pf[s] = __builtin_bit_cast(bf16x8, pk);
;       }
; #pragma unroll
;       for (int mb = 0; mb < NMB; ++mb)
; #pragma unroll
;         for (int s = 0; s < 2; ++s) {
;           const u16* vpp = ldsV + (mb * 32 + l31) * 72 + kh * 32 + 16 * s + 4 * h2;
;           const s16x4 lo = *(const s16x4*)(vpp);
;           const s16x4 hi = *(const s16x4*)(vpp + 8);
;           const bf16x8 vf = __builtin_shufflevector(lo, hi, 0, 1, 2, 3, 4, 5, 6, 7);
;           o[mb] = MFMA32(vf, pf[s], o[mb]);
;         }
.LBB0_1366:
	v_sub_f32_e32 v2, v80, v8
	v_exp_f32_e32 v2, v2
	v_sub_f32_e32 v4, v81, v8
	v_exp_f32_e32 v4, v4
	v_sub_f32_e32 v5, v82, v8
	v_exp_f32_e32 v5, v5
	v_sub_f32_e32 v9, v83, v8
	v_exp_f32_e32 v9, v9
	v_sub_f32_e32 v10, v84, v8
	v_add_f32_e32 v3, 0, v2
	v_exp_f32_e32 v12, v10
	v_sub_f32_e32 v10, v85, v8
	v_add_f32_e32 v3, v4, v3
	v_exp_f32_e32 v13, v10
	v_sub_f32_e32 v10, v86, v8
	v_add_f32_e32 v3, v5, v3
	v_exp_f32_e32 v14, v10
	v_sub_f32_e32 v10, v87, v8
	v_add_f32_e32 v3, v9, v3
	v_exp_f32_e32 v15, v10
	v_sub_f32_e32 v10, v88, v8
	v_add_f32_e32 v3, v12, v3
	v_exp_f32_e32 v80, v10
	v_sub_f32_e32 v10, v89, v8
	v_add_f32_e32 v3, v13, v3
	v_exp_f32_e32 v81, v10
	v_sub_f32_e32 v10, v90, v8
	v_add_f32_e32 v3, v14, v3
	v_exp_f32_e32 v82, v10
	v_sub_f32_e32 v10, v91, v8
	v_add_f32_e32 v3, v15, v3
	v_exp_f32_e32 v83, v10
	v_sub_f32_e32 v10, v92, v8
	v_add_f32_e32 v3, v80, v3
	v_exp_f32_e32 v84, v10
	v_sub_f32_e32 v10, v93, v8
	v_add_f32_e32 v3, v81, v3
	v_exp_f32_e32 v85, v10
	v_sub_f32_e32 v10, v94, v8
	v_add_f32_e32 v3, v82, v3
	v_exp_f32_e32 v86, v10
	v_sub_f32_e32 v10, v95, v8
	v_add_f32_e32 v3, v83, v3
	v_exp_f32_e32 v87, v10
	v_add_f32_e32 v3, v84, v3
	v_add_f32_e32 v3, v85, v3
	v_add_f32_e32 v3, v86, v3
	v_add_f32_e32 v88, v87, v3
	v_fmac_f32_e32 v88, v205, v0
	v_add_u32_e32 v0, v6, v204
	v_cvt_pk_bf16_f32 v11, v5, v9
	v_add_u32_e32 v9, 0x6000, v0
	v_cvt_pk_bf16_f32 v10, v2, v4
	v_cvt_pk_bf16_f32 v2, v80, v81
	v_cvt_pk_bf16_f32 v3, v82, v83
	v_cvt_pk_bf16_f32 v4, v84, v85
	v_cvt_pk_bf16_f32 v5, v86, v87
	v_cvt_pk_bf16_f32 v12, v12, v13
	v_cvt_pk_bf16_f32 v13, v14, v15
	v_add_u32_e32 v9, 0x7000, v0
	v_mov_b32_e32 v206, v8
	s_waitcnt lgkmcnt(0)
	v_mfma_f32_32x32x16_bf16 v[64:79], v[232:235], v[10:13], v[64:79]
	v_mov_b32_e32 v205, v88
	v_mfma_f32_32x32x16_bf16 v[48:63], v[240:243], v[10:13], v[48:63]
	v_add_u32_e32 v9, 0x8800, v0
	v_add_u32_e32 v0, 0x9800, v0
	v_mfma_f32_32x32x16_bf16 v[48:63], v[244:247], v[2:5], v[48:63]
	v_mfma_f32_32x32x16_bf16 v[32:47], v[248:251], v[10:13], v[32:47]
	v_mfma_f32_32x32x16_bf16 v[32:47], v[208:211], v[2:5], v[32:47]
	v_mfma_f32_32x32x16_bf16 v[16:31], v[212:215], v[10:13], v[16:31]
	v_mfma_f32_32x32x16_bf16 v[64:79], v[236:239], v[2:5], v[64:79]
	v_mfma_f32_32x32x16_bf16 v[16:31], v[216:219], v[2:5], v[16:31]
.LBB0_1367:
	s_or_b64 exec, exec, s[40:41]
	s_add_i32 s40, s72, 32
	v_cmp_le_i32_e32 vcc, s40, v202
	s_and_saveexec_b64 s[40:41], vcc
	s_cbranch_execz .LBB0_1356
	ds_read_b128 v[232:235], v7 offset:12800
	ds_read_b128 v[236:239], v7 offset:12832
	ds_read_b128 v[240:243], v7 offset:12864
	ds_read_b128 v[244:247], v7 offset:12896
	ds_read_b128 v[248:251], v7 offset:12928
	ds_read_b128 v[208:211], v7 offset:12960
	s_add_i32 s48, s72, 63
	v_cmp_gt_i32_e32 vcc, s48, v193
	s_waitcnt lgkmcnt(5)
	v_mfma_f32_32x32x16_bf16 v[80:95], v[232:235], v[96:99], 0
	ds_read_b128 v[232:235], v7 offset:12992
	s_waitcnt lgkmcnt(5)
	v_mfma_f32_32x32x16_bf16 v[80:95], v[236:239], v[100:103], v[80:95]
	ds_read_b128 v[236:239], v7 offset:13024
	s_waitcnt lgkmcnt(5)
	v_mfma_f32_32x32x16_bf16 v[80:95], v[240:243], v[104:107], v[80:95]
	ds_read_b128 v[240:243], v7 offset:13056
	s_waitcnt lgkmcnt(5)
	v_mfma_f32_32x32x16_bf16 v[80:95], v[244:247], v[108:111], v[80:95]
	ds_read_b128 v[244:247], v7 offset:13088
	s_waitcnt lgkmcnt(5)
	v_mfma_f32_32x32x16_bf16 v[80:95], v[248:251], v[112:115], v[80:95]
	ds_read_b128 v[248:251], v7 offset:13120
	s_waitcnt lgkmcnt(5)
	v_mfma_f32_32x32x16_bf16 v[80:95], v[208:211], v[116:119], v[80:95]
	ds_read_b128 v[208:211], v7 offset:13152
	s_waitcnt lgkmcnt(5)
	v_mfma_f32_32x32x16_bf16 v[80:95], v[232:235], v[120:123], v[80:95]
	s_waitcnt lgkmcnt(4)
	v_mfma_f32_32x32x16_bf16 v[80:95], v[236:239], v[124:127], v[80:95]
	s_waitcnt lgkmcnt(3)
	v_mfma_f32_32x32x16_bf16 v[80:95], v[240:243], v[128:131], v[80:95]
	s_waitcnt lgkmcnt(2)
	v_mfma_f32_32x32x16_bf16 v[80:95], v[244:247], v[132:135], v[80:95]
	s_waitcnt lgkmcnt(1)
	v_mfma_f32_32x32x16_bf16 v[80:95], v[248:251], v[136:139], v[80:95]
	s_waitcnt lgkmcnt(0)
	v_mfma_f32_32x32x16_bf16 v[80:95], v[208:211], v[140:143], v[80:95]
	v_add_u32_e32 v221, v6, v204
	v_add_u32_e32 v222, 0x6000, v221
	v_add_u32_e32 v223, 0x7000, v221
	v_add_u32_e32 v224, 0x8800, v221
	v_add_u32_e32 v225, 0x9800, v221
	ds_read2_b64 v[232:235], v222 offset0:136 offset1:138
	ds_read2_b64 v[236:239], v222 offset0:140 offset1:142
	ds_read2_b64 v[240:243], v223 offset0:200 offset1:202
	ds_read2_b64 v[244:247], v223 offset0:204 offset1:206
	ds_read2_b64 v[248:251], v224 offset0:8 offset1:10
	ds_read2_b64 v[208:211], v224 offset0:12 offset1:14
	ds_read2_b64 v[212:215], v225 offset0:72 offset1:74
	ds_read2_b64 v[216:219], v225 offset0:76 offset1:78
	s_and_saveexec_b64 s[48:49], vcc
	s_cbranch_execz .LBB0_1370
	v_add_u32_e32 v0, s72, v196
	v_add_u32_e32 v2, 32, v0
	v_cmp_lt_i32_e32 vcc, v2, v166
	s_nop 6
	v_cndmask_b32_e32 v81, v229, v81, vcc
	v_cmp_le_i32_e32 vcc, v2, v166
	v_add_u32_e32 v2, 34, v0
	s_nop 0
	v_cndmask_b32_e32 v80, v229, v80, vcc
	v_cmp_le_i32_e32 vcc, v2, v166
	v_add_u32_e32 v2, 35, v0
	s_nop 0
	v_cndmask_b32_e32 v82, v229, v82, vcc
	v_cmp_le_i32_e32 vcc, v2, v166
	v_add_u32_e32 v2, 40, v0
	s_nop 0
	v_cndmask_b32_e32 v83, v229, v83, vcc
	v_cmp_le_i32_e32 vcc, v2, v166
	v_add_u32_e32 v2, 41, v0
	s_nop 0
	v_cndmask_b32_e32 v84, v229, v84, vcc
	v_cmp_le_i32_e32 vcc, v2, v166
	v_add_u32_e32 v2, 42, v0
	s_nop 0
	v_cndmask_b32_e32 v85, v229, v85, vcc
	v_cmp_le_i32_e32 vcc, v2, v166
	v_add_u32_e32 v2, 43, v0
	s_nop 0
	v_cndmask_b32_e32 v86, v229, v86, vcc
	v_cmp_le_i32_e32 vcc, v2, v166
	v_add_u32_e32 v2, 48, v0
	s_nop 0
	v_cndmask_b32_e32 v87, v229, v87, vcc
	v_cmp_le_i32_e32 vcc, v2, v166
	v_add_u32_e32 v2, 49, v0
	s_nop 0
	v_cndmask_b32_e32 v88, v229, v88, vcc
	v_cmp_le_i32_e32 vcc, v2, v166
	v_add_u32_e32 v2, 50, v0
	s_nop 0
	v_cndmask_b32_e32 v89, v229, v89, vcc
	v_cmp_le_i32_e32 vcc, v2, v166
	v_add_u32_e32 v2, 51, v0
	s_nop 0
	v_cndmask_b32_e32 v90, v229, v90, vcc
	v_cmp_le_i32_e32 vcc, v2, v166
	v_add_u32_e32 v2, 56, v0
	s_nop 0
	v_cndmask_b32_e32 v91, v229, v91, vcc
	v_cmp_le_i32_e32 vcc, v2, v166
	v_add_u32_e32 v2, 57, v0
	s_nop 0
	v_cndmask_b32_e32 v92, v229, v92, vcc
	v_cmp_le_i32_e32 vcc, v2, v166
	v_add_u32_e32 v2, 58, v0
	v_add_u32_e32 v0, 59, v0
	v_cndmask_b32_e32 v93, v229, v93, vcc
	v_cmp_le_i32_e32 vcc, v2, v166
	s_nop 1
	v_cndmask_b32_e32 v94, v229, v94, vcc
	v_cmp_le_i32_e32 vcc, v0, v166
	s_nop 1
	v_cndmask_b32_e32 v95, v229, v95, vcc
